# mlstm_a2 normaliser scan: all 96 loads of the 32-chunk recurrence issued ahead (was three loads + wait per chunk), stores after the recurrence
# baseline (speedup 1.0000x reference)
.LBB0_585:
	v_lshl_add_u64 v[10:11], v[2:3], 0, s[4:5]
	v_add_co_u32_e32 v8, vcc, 0x1ae84000, v10
	v_lshl_add_u64 v[6:7], v[4:5], 0, s[4:5]
	s_nop 0
	v_addc_co_u32_e32 v9, vcc, 0, v11, vcc
	v_add_co_u32_e32 v10, vcc, 0x1ae85000, v10
	s_nop 1
	v_addc_co_u32_e32 v11, vcc, 0, v11, vcc
	s_mov_b64 s[18:19], 0x1000
	v_lshl_add_u64 v[88:89], v[6:7], 0, s[18:19]
	s_mov_b64 s[18:19], 0x2000
	v_lshl_add_u64 v[90:91], v[6:7], 0, s[18:19]
	s_mov_b64 s[18:19], 0x3000
	v_lshl_add_u64 v[92:93], v[6:7], 0, s[18:19]
	global_load_dword v204, v[6:7], off offset:-1024
	global_load_dword v16, v[8:9], off
	global_load_dword v166, v[10:11], off
	global_load_dword v205, v[6:7], off offset:-512
	global_load_dword v17, v[8:9], off offset:4
	global_load_dword v167, v[10:11], off offset:4
	global_load_dword v206, v[6:7], off
	global_load_dword v18, v[8:9], off offset:8
	global_load_dword v168, v[10:11], off offset:8
	global_load_dword v207, v[6:7], off offset:512
	global_load_dword v19, v[8:9], off offset:12
	global_load_dword v169, v[10:11], off offset:12
	global_load_dword v208, v[6:7], off offset:1024
	global_load_dword v20, v[8:9], off offset:16
	global_load_dword v170, v[10:11], off offset:16
	global_load_dword v209, v[6:7], off offset:1536
	global_load_dword v21, v[8:9], off offset:20
	global_load_dword v171, v[10:11], off offset:20
	global_load_dword v210, v[6:7], off offset:2048
	global_load_dword v22, v[8:9], off offset:24
	global_load_dword v172, v[10:11], off offset:24
	global_load_dword v211, v[6:7], off offset:2560
	global_load_dword v23, v[8:9], off offset:28
	global_load_dword v173, v[10:11], off offset:28
	global_load_dword v212, v[88:89], off offset:-1024
	global_load_dword v24, v[8:9], off offset:32
	global_load_dword v174, v[10:11], off offset:32
	global_load_dword v213, v[88:89], off offset:-512
	global_load_dword v25, v[8:9], off offset:36
	global_load_dword v175, v[10:11], off offset:36
	global_load_dword v214, v[88:89], off
	global_load_dword v26, v[8:9], off offset:40
	global_load_dword v176, v[10:11], off offset:40
	global_load_dword v215, v[88:89], off offset:512
	global_load_dword v27, v[8:9], off offset:44
	global_load_dword v177, v[10:11], off offset:44
	global_load_dword v216, v[88:89], off offset:1024
	global_load_dword v28, v[8:9], off offset:48
	global_load_dword v178, v[10:11], off offset:48
	global_load_dword v217, v[88:89], off offset:1536
	global_load_dword v29, v[8:9], off offset:52
	global_load_dword v179, v[10:11], off offset:52
	global_load_dword v218, v[88:89], off offset:2048
	global_load_dword v30, v[8:9], off offset:56
	global_load_dword v180, v[10:11], off offset:56
	global_load_dword v219, v[88:89], off offset:2560
	global_load_dword v31, v[8:9], off offset:60
	global_load_dword v181, v[10:11], off offset:60
	global_load_dword v220, v[90:91], off offset:-1024
	global_load_dword v32, v[8:9], off offset:64
	global_load_dword v182, v[10:11], off offset:64
	global_load_dword v221, v[90:91], off offset:-512
	global_load_dword v33, v[8:9], off offset:68
	global_load_dword v183, v[10:11], off offset:68
	global_load_dword v222, v[90:91], off
	global_load_dword v34, v[8:9], off offset:72
	global_load_dword v184, v[10:11], off offset:72
	global_load_dword v223, v[90:91], off offset:512
	global_load_dword v35, v[8:9], off offset:76
	global_load_dword v185, v[10:11], off offset:76
	s_waitcnt vmcnt(57)
	v_mov_b32_e32 v236, v12
	v_add_f32_e32 v0, v0, v16
	v_max_f32_e32 v14, v166, v166
	v_max_f32_e32 v14, v0, v14
	v_sub_f32_e32 v15, v166, v14
	v_sub_f32_e32 v0, v0, v14
	v_mul_f32_e32 v15, 0x3fb8aa3b, v15
	v_mul_f32_e32 v0, 0x3fb8aa3b, v0
	v_exp_f32_e32 v15, v15
	v_exp_f32_e32 v0, v0
	v_mul_f32_e32 v13, v204, v15
	v_fmac_f32_e32 v13, v12, v0
	v_mov_b32_e32 v12, v13
	v_mov_b32_e32 v0, v14
	s_waitcnt vmcnt(54)
	v_mov_b32_e32 v237, v12
	v_add_f32_e32 v0, v0, v17
	v_max_f32_e32 v14, v167, v167
	v_max_f32_e32 v14, v0, v14
	v_sub_f32_e32 v15, v167, v14
	v_sub_f32_e32 v0, v0, v14
	v_mul_f32_e32 v15, 0x3fb8aa3b, v15
	v_mul_f32_e32 v0, 0x3fb8aa3b, v0
	v_exp_f32_e32 v15, v15
	v_exp_f32_e32 v0, v0
	v_mul_f32_e32 v13, v205, v15
	v_fmac_f32_e32 v13, v12, v0
	v_mov_b32_e32 v12, v13
	v_mov_b32_e32 v0, v14
	s_waitcnt vmcnt(51)
	v_mov_b32_e32 v238, v12
	v_add_f32_e32 v0, v0, v18
	v_max_f32_e32 v14, v168, v168
	v_max_f32_e32 v14, v0, v14
	v_sub_f32_e32 v15, v168, v14
	v_sub_f32_e32 v0, v0, v14
	v_mul_f32_e32 v15, 0x3fb8aa3b, v15
	v_mul_f32_e32 v0, 0x3fb8aa3b, v0
	v_exp_f32_e32 v15, v15
	v_exp_f32_e32 v0, v0
	v_mul_f32_e32 v13, v206, v15
	v_fmac_f32_e32 v13, v12, v0
	v_mov_b32_e32 v12, v13
	v_mov_b32_e32 v0, v14
	s_waitcnt vmcnt(48)
	v_mov_b32_e32 v239, v12
	v_add_f32_e32 v0, v0, v19
	v_max_f32_e32 v14, v169, v169
	v_max_f32_e32 v14, v0, v14
	v_sub_f32_e32 v15, v169, v14
	v_sub_f32_e32 v0, v0, v14
	v_mul_f32_e32 v15, 0x3fb8aa3b, v15
	v_mul_f32_e32 v0, 0x3fb8aa3b, v0
	v_exp_f32_e32 v15, v15
	v_exp_f32_e32 v0, v0
	v_mul_f32_e32 v13, v207, v15
	v_fmac_f32_e32 v13, v12, v0
	v_mov_b32_e32 v12, v13
	v_mov_b32_e32 v0, v14
	s_waitcnt vmcnt(45)
	v_mov_b32_e32 v240, v12
	v_add_f32_e32 v0, v0, v20
	v_max_f32_e32 v14, v170, v170
	v_max_f32_e32 v14, v0, v14
	v_sub_f32_e32 v15, v170, v14
	v_sub_f32_e32 v0, v0, v14
	v_mul_f32_e32 v15, 0x3fb8aa3b, v15
	v_mul_f32_e32 v0, 0x3fb8aa3b, v0
	v_exp_f32_e32 v15, v15
	v_exp_f32_e32 v0, v0
	v_mul_f32_e32 v13, v208, v15
	v_fmac_f32_e32 v13, v12, v0
	v_mov_b32_e32 v12, v13
	v_mov_b32_e32 v0, v14
	s_waitcnt vmcnt(42)
	v_mov_b32_e32 v241, v12
	v_add_f32_e32 v0, v0, v21
	v_max_f32_e32 v14, v171, v171
	v_max_f32_e32 v14, v0, v14
	v_sub_f32_e32 v15, v171, v14
	v_sub_f32_e32 v0, v0, v14
	v_mul_f32_e32 v15, 0x3fb8aa3b, v15
	v_mul_f32_e32 v0, 0x3fb8aa3b, v0
	v_exp_f32_e32 v15, v15
	v_exp_f32_e32 v0, v0
	v_mul_f32_e32 v13, v209, v15
	v_fmac_f32_e32 v13, v12, v0
	v_mov_b32_e32 v12, v13
	v_mov_b32_e32 v0, v14
	s_waitcnt vmcnt(39)
	v_mov_b32_e32 v242, v12
	v_add_f32_e32 v0, v0, v22
	v_max_f32_e32 v14, v172, v172
	v_max_f32_e32 v14, v0, v14
	v_sub_f32_e32 v15, v172, v14
	v_sub_f32_e32 v0, v0, v14
	v_mul_f32_e32 v15, 0x3fb8aa3b, v15
	v_mul_f32_e32 v0, 0x3fb8aa3b, v0
	v_exp_f32_e32 v15, v15
	v_exp_f32_e32 v0, v0
	v_mul_f32_e32 v13, v210, v15
	v_fmac_f32_e32 v13, v12, v0
	v_mov_b32_e32 v12, v13
	v_mov_b32_e32 v0, v14
	s_waitcnt vmcnt(36)
	v_mov_b32_e32 v243, v12
	v_add_f32_e32 v0, v0, v23
	v_max_f32_e32 v14, v173, v173
	v_max_f32_e32 v14, v0, v14
	v_sub_f32_e32 v15, v173, v14
	v_sub_f32_e32 v0, v0, v14
	v_mul_f32_e32 v15, 0x3fb8aa3b, v15
	v_mul_f32_e32 v0, 0x3fb8aa3b, v0
	v_exp_f32_e32 v15, v15
	v_exp_f32_e32 v0, v0
	v_mul_f32_e32 v13, v211, v15
	v_fmac_f32_e32 v13, v12, v0
	v_mov_b32_e32 v12, v13
	v_mov_b32_e32 v0, v14
	s_waitcnt vmcnt(33)
	v_mov_b32_e32 v244, v12
	v_add_f32_e32 v0, v0, v24
	v_max_f32_e32 v14, v174, v174
	v_max_f32_e32 v14, v0, v14
	v_sub_f32_e32 v15, v174, v14
	v_sub_f32_e32 v0, v0, v14
	v_mul_f32_e32 v15, 0x3fb8aa3b, v15
	v_mul_f32_e32 v0, 0x3fb8aa3b, v0
	v_exp_f32_e32 v15, v15
	v_exp_f32_e32 v0, v0
	v_mul_f32_e32 v13, v212, v15
	v_fmac_f32_e32 v13, v12, v0
	v_mov_b32_e32 v12, v13
	v_mov_b32_e32 v0, v14
	s_waitcnt vmcnt(30)
	v_mov_b32_e32 v245, v12
	v_add_f32_e32 v0, v0, v25
	v_max_f32_e32 v14, v175, v175
	v_max_f32_e32 v14, v0, v14
	v_sub_f32_e32 v15, v175, v14
	v_sub_f32_e32 v0, v0, v14
	v_mul_f32_e32 v15, 0x3fb8aa3b, v15
	v_mul_f32_e32 v0, 0x3fb8aa3b, v0
	v_exp_f32_e32 v15, v15
	v_exp_f32_e32 v0, v0
	v_mul_f32_e32 v13, v213, v15
	v_fmac_f32_e32 v13, v12, v0
	v_mov_b32_e32 v12, v13
	v_mov_b32_e32 v0, v14
	s_waitcnt vmcnt(27)
	v_mov_b32_e32 v246, v12
	v_add_f32_e32 v0, v0, v26
	v_max_f32_e32 v14, v176, v176
	v_max_f32_e32 v14, v0, v14
	v_sub_f32_e32 v15, v176, v14
	v_sub_f32_e32 v0, v0, v14
	v_mul_f32_e32 v15, 0x3fb8aa3b, v15
	v_mul_f32_e32 v0, 0x3fb8aa3b, v0
	v_exp_f32_e32 v15, v15
	v_exp_f32_e32 v0, v0
	v_mul_f32_e32 v13, v214, v15
	v_fmac_f32_e32 v13, v12, v0
	v_mov_b32_e32 v12, v13
	v_mov_b32_e32 v0, v14
	global_load_dword v224, v[90:91], off offset:1024
	global_load_dword v96, v[8:9], off offset:80
	global_load_dword v186, v[10:11], off offset:80
	global_load_dword v225, v[90:91], off offset:1536
	global_load_dword v97, v[8:9], off offset:84
	global_load_dword v187, v[10:11], off offset:84
	global_load_dword v226, v[90:91], off offset:2048
	global_load_dword v98, v[8:9], off offset:88
	global_load_dword v188, v[10:11], off offset:88
	global_load_dword v227, v[90:91], off offset:2560
	global_load_dword v99, v[8:9], off offset:92
	global_load_dword v189, v[10:11], off offset:92
	global_load_dword v228, v[92:93], off offset:-1024
	global_load_dword v100, v[8:9], off offset:96
	global_load_dword v190, v[10:11], off offset:96
	global_load_dword v229, v[92:93], off offset:-512
	global_load_dword v101, v[8:9], off offset:100
	global_load_dword v191, v[10:11], off offset:100
	global_load_dword v230, v[92:93], off
	global_load_dword v102, v[8:9], off offset:104
	global_load_dword v108, v[10:11], off offset:104
	global_load_dword v231, v[92:93], off offset:512
	global_load_dword v103, v[8:9], off offset:108
	global_load_dword v109, v[10:11], off offset:108
	global_load_dword v232, v[92:93], off offset:1024
	global_load_dword v104, v[8:9], off offset:112
	global_load_dword v110, v[10:11], off offset:112
	global_load_dword v233, v[92:93], off offset:1536
	global_load_dword v105, v[8:9], off offset:116
	global_load_dword v111, v[10:11], off offset:116
	global_load_dword v234, v[92:93], off offset:2048
	global_load_dword v106, v[8:9], off offset:120
	global_load_dword v112, v[10:11], off offset:120
	global_load_dword v235, v[92:93], off offset:2560
	global_load_dword v107, v[8:9], off offset:124
	global_load_dword v113, v[10:11], off offset:124
	s_waitcnt vmcnt(60)
	v_mov_b32_e32 v247, v12
	v_add_f32_e32 v0, v0, v27
	v_max_f32_e32 v14, v177, v177
	v_max_f32_e32 v14, v0, v14
	v_sub_f32_e32 v15, v177, v14
	v_sub_f32_e32 v0, v0, v14
	v_mul_f32_e32 v15, 0x3fb8aa3b, v15
	v_mul_f32_e32 v0, 0x3fb8aa3b, v0
	v_exp_f32_e32 v15, v15
	v_exp_f32_e32 v0, v0
	v_mul_f32_e32 v13, v215, v15
	v_fmac_f32_e32 v13, v12, v0
	v_mov_b32_e32 v12, v13
	v_mov_b32_e32 v0, v14
	s_waitcnt vmcnt(57)
	v_mov_b32_e32 v248, v12
	v_add_f32_e32 v0, v0, v28
	v_max_f32_e32 v14, v178, v178
	v_max_f32_e32 v14, v0, v14
	v_sub_f32_e32 v15, v178, v14
	v_sub_f32_e32 v0, v0, v14
	v_mul_f32_e32 v15, 0x3fb8aa3b, v15
	v_mul_f32_e32 v0, 0x3fb8aa3b, v0
	v_exp_f32_e32 v15, v15
	v_exp_f32_e32 v0, v0
	v_mul_f32_e32 v13, v216, v15
	v_fmac_f32_e32 v13, v12, v0
	v_mov_b32_e32 v12, v13
	v_mov_b32_e32 v0, v14
	s_waitcnt vmcnt(54)
	v_mov_b32_e32 v249, v12
	v_add_f32_e32 v0, v0, v29
	v_max_f32_e32 v14, v179, v179
	v_max_f32_e32 v14, v0, v14
	v_sub_f32_e32 v15, v179, v14
	v_sub_f32_e32 v0, v0, v14
	v_mul_f32_e32 v15, 0x3fb8aa3b, v15
	v_mul_f32_e32 v0, 0x3fb8aa3b, v0
	v_exp_f32_e32 v15, v15
	v_exp_f32_e32 v0, v0
	v_mul_f32_e32 v13, v217, v15
	v_fmac_f32_e32 v13, v12, v0
	v_mov_b32_e32 v12, v13
	v_mov_b32_e32 v0, v14
	s_waitcnt vmcnt(51)
	v_mov_b32_e32 v250, v12
	v_add_f32_e32 v0, v0, v30
	v_max_f32_e32 v14, v180, v180
	v_max_f32_e32 v14, v0, v14
	v_sub_f32_e32 v15, v180, v14
	v_sub_f32_e32 v0, v0, v14
	v_mul_f32_e32 v15, 0x3fb8aa3b, v15
	v_mul_f32_e32 v0, 0x3fb8aa3b, v0
	v_exp_f32_e32 v15, v15
	v_exp_f32_e32 v0, v0
	v_mul_f32_e32 v13, v218, v15
	v_fmac_f32_e32 v13, v12, v0
	v_mov_b32_e32 v12, v13
	v_mov_b32_e32 v0, v14
	s_waitcnt vmcnt(48)
	v_mov_b32_e32 v251, v12
	v_add_f32_e32 v0, v0, v31
	v_max_f32_e32 v14, v181, v181
	v_max_f32_e32 v14, v0, v14
	v_sub_f32_e32 v15, v181, v14
	v_sub_f32_e32 v0, v0, v14
	v_mul_f32_e32 v15, 0x3fb8aa3b, v15
	v_mul_f32_e32 v0, 0x3fb8aa3b, v0
	v_exp_f32_e32 v15, v15
	v_exp_f32_e32 v0, v0
	v_mul_f32_e32 v13, v219, v15
	v_fmac_f32_e32 v13, v12, v0
	v_mov_b32_e32 v12, v13
	v_mov_b32_e32 v0, v14
	s_waitcnt vmcnt(45)
	v_mov_b32_e32 v132, v12
	v_add_f32_e32 v0, v0, v32
	v_max_f32_e32 v14, v182, v182
	v_max_f32_e32 v14, v0, v14
	v_sub_f32_e32 v15, v182, v14
	v_sub_f32_e32 v0, v0, v14
	v_mul_f32_e32 v15, 0x3fb8aa3b, v15
	v_mul_f32_e32 v0, 0x3fb8aa3b, v0
	v_exp_f32_e32 v15, v15
	v_exp_f32_e32 v0, v0
	v_mul_f32_e32 v13, v220, v15
	v_fmac_f32_e32 v13, v12, v0
	v_mov_b32_e32 v12, v13
	v_mov_b32_e32 v0, v14
	s_waitcnt vmcnt(42)
	v_mov_b32_e32 v133, v12
	v_add_f32_e32 v0, v0, v33
	v_max_f32_e32 v14, v183, v183
	v_max_f32_e32 v14, v0, v14
	v_sub_f32_e32 v15, v183, v14
	v_sub_f32_e32 v0, v0, v14
	v_mul_f32_e32 v15, 0x3fb8aa3b, v15
	v_mul_f32_e32 v0, 0x3fb8aa3b, v0
	v_exp_f32_e32 v15, v15
	v_exp_f32_e32 v0, v0
	v_mul_f32_e32 v13, v221, v15
	v_fmac_f32_e32 v13, v12, v0
	v_mov_b32_e32 v12, v13
	v_mov_b32_e32 v0, v14
	s_waitcnt vmcnt(39)
	v_mov_b32_e32 v134, v12
	v_add_f32_e32 v0, v0, v34
	v_max_f32_e32 v14, v184, v184
	v_max_f32_e32 v14, v0, v14
	v_sub_f32_e32 v15, v184, v14
	v_sub_f32_e32 v0, v0, v14
	v_mul_f32_e32 v15, 0x3fb8aa3b, v15
	v_mul_f32_e32 v0, 0x3fb8aa3b, v0
	v_exp_f32_e32 v15, v15
	v_exp_f32_e32 v0, v0
	v_mul_f32_e32 v13, v222, v15
	v_fmac_f32_e32 v13, v12, v0
	v_mov_b32_e32 v12, v13
	v_mov_b32_e32 v0, v14
	s_waitcnt vmcnt(36)
	v_mov_b32_e32 v135, v12
	v_add_f32_e32 v0, v0, v35
	v_max_f32_e32 v14, v185, v185
	v_max_f32_e32 v14, v0, v14
	v_sub_f32_e32 v15, v185, v14
	v_sub_f32_e32 v0, v0, v14
	v_mul_f32_e32 v15, 0x3fb8aa3b, v15
	v_mul_f32_e32 v0, 0x3fb8aa3b, v0
	v_exp_f32_e32 v15, v15
	v_exp_f32_e32 v0, v0
	v_mul_f32_e32 v13, v223, v15
	v_fmac_f32_e32 v13, v12, v0
	v_mov_b32_e32 v12, v13
	v_mov_b32_e32 v0, v14
	s_waitcnt vmcnt(33)
	v_mov_b32_e32 v136, v12
	v_add_f32_e32 v0, v0, v96
	v_max_f32_e32 v14, v186, v186
	v_max_f32_e32 v14, v0, v14
	v_sub_f32_e32 v15, v186, v14
	v_sub_f32_e32 v0, v0, v14
	v_mul_f32_e32 v15, 0x3fb8aa3b, v15
	v_mul_f32_e32 v0, 0x3fb8aa3b, v0
	v_exp_f32_e32 v15, v15
	v_exp_f32_e32 v0, v0
	v_mul_f32_e32 v13, v224, v15
	v_fmac_f32_e32 v13, v12, v0
	v_mov_b32_e32 v12, v13
	v_mov_b32_e32 v0, v14
	s_waitcnt vmcnt(30)
	v_mov_b32_e32 v137, v12
	v_add_f32_e32 v0, v0, v97
	v_max_f32_e32 v14, v187, v187
	v_max_f32_e32 v14, v0, v14
	v_sub_f32_e32 v15, v187, v14
	v_sub_f32_e32 v0, v0, v14
	v_mul_f32_e32 v15, 0x3fb8aa3b, v15
	v_mul_f32_e32 v0, 0x3fb8aa3b, v0
	v_exp_f32_e32 v15, v15
	v_exp_f32_e32 v0, v0
	v_mul_f32_e32 v13, v225, v15
	v_fmac_f32_e32 v13, v12, v0
	v_mov_b32_e32 v12, v13
	v_mov_b32_e32 v0, v14
	s_waitcnt vmcnt(27)
	v_mov_b32_e32 v46, v12
	v_add_f32_e32 v0, v0, v98
	v_max_f32_e32 v14, v188, v188
	v_max_f32_e32 v14, v0, v14
	v_sub_f32_e32 v15, v188, v14
	v_sub_f32_e32 v0, v0, v14
	v_mul_f32_e32 v15, 0x3fb8aa3b, v15
	v_mul_f32_e32 v0, 0x3fb8aa3b, v0
	v_exp_f32_e32 v15, v15
	v_exp_f32_e32 v0, v0
	v_mul_f32_e32 v13, v226, v15
	v_fmac_f32_e32 v13, v12, v0
	v_mov_b32_e32 v12, v13
	v_mov_b32_e32 v0, v14
	s_waitcnt vmcnt(24)
	v_mov_b32_e32 v47, v12
	v_add_f32_e32 v0, v0, v99
	v_max_f32_e32 v14, v189, v189
	v_max_f32_e32 v14, v0, v14
	v_sub_f32_e32 v15, v189, v14
	v_sub_f32_e32 v0, v0, v14
	v_mul_f32_e32 v15, 0x3fb8aa3b, v15
	v_mul_f32_e32 v0, 0x3fb8aa3b, v0
	v_exp_f32_e32 v15, v15
	v_exp_f32_e32 v0, v0
	v_mul_f32_e32 v13, v227, v15
	v_fmac_f32_e32 v13, v12, v0
	v_mov_b32_e32 v12, v13
	v_mov_b32_e32 v0, v14
	s_waitcnt vmcnt(21)
	v_mov_b32_e32 v48, v12
	v_add_f32_e32 v0, v0, v100
	v_max_f32_e32 v14, v190, v190
	v_max_f32_e32 v14, v0, v14
	v_sub_f32_e32 v15, v190, v14
	v_sub_f32_e32 v0, v0, v14
	v_mul_f32_e32 v15, 0x3fb8aa3b, v15
	v_mul_f32_e32 v0, 0x3fb8aa3b, v0
	v_exp_f32_e32 v15, v15
	v_exp_f32_e32 v0, v0
	v_mul_f32_e32 v13, v228, v15
	v_fmac_f32_e32 v13, v12, v0
	v_mov_b32_e32 v12, v13
	v_mov_b32_e32 v0, v14
	s_waitcnt vmcnt(18)
	v_mov_b32_e32 v49, v12
	v_add_f32_e32 v0, v0, v101
	v_max_f32_e32 v14, v191, v191
	v_max_f32_e32 v14, v0, v14
	v_sub_f32_e32 v15, v191, v14
	v_sub_f32_e32 v0, v0, v14
	v_mul_f32_e32 v15, 0x3fb8aa3b, v15
	v_mul_f32_e32 v0, 0x3fb8aa3b, v0
	v_exp_f32_e32 v15, v15
	v_exp_f32_e32 v0, v0
	v_mul_f32_e32 v13, v229, v15
	v_fmac_f32_e32 v13, v12, v0
	v_mov_b32_e32 v12, v13
	v_mov_b32_e32 v0, v14
	s_waitcnt vmcnt(15)
	v_mov_b32_e32 v65, v12
	v_add_f32_e32 v0, v0, v102
	v_max_f32_e32 v14, v108, v108
	v_max_f32_e32 v14, v0, v14
	v_sub_f32_e32 v15, v108, v14
	v_sub_f32_e32 v0, v0, v14
	v_mul_f32_e32 v15, 0x3fb8aa3b, v15
	v_mul_f32_e32 v0, 0x3fb8aa3b, v0
	v_exp_f32_e32 v15, v15
	v_exp_f32_e32 v0, v0
	v_mul_f32_e32 v13, v230, v15
	v_fmac_f32_e32 v13, v12, v0
	v_mov_b32_e32 v12, v13
	v_mov_b32_e32 v0, v14
	s_waitcnt vmcnt(12)
	v_mov_b32_e32 v66, v12
	v_add_f32_e32 v0, v0, v103
	v_max_f32_e32 v14, v109, v109
	v_max_f32_e32 v14, v0, v14
	v_sub_f32_e32 v15, v109, v14
	v_sub_f32_e32 v0, v0, v14
	v_mul_f32_e32 v15, 0x3fb8aa3b, v15
	v_mul_f32_e32 v0, 0x3fb8aa3b, v0
	v_exp_f32_e32 v15, v15
	v_exp_f32_e32 v0, v0
	v_mul_f32_e32 v13, v231, v15
	v_fmac_f32_e32 v13, v12, v0
	v_mov_b32_e32 v12, v13
	v_mov_b32_e32 v0, v14
	s_waitcnt vmcnt(9)
	v_mov_b32_e32 v67, v12
	v_add_f32_e32 v0, v0, v104
	v_max_f32_e32 v14, v110, v110
	v_max_f32_e32 v14, v0, v14
	v_sub_f32_e32 v15, v110, v14
	v_sub_f32_e32 v0, v0, v14
	v_mul_f32_e32 v15, 0x3fb8aa3b, v15
	v_mul_f32_e32 v0, 0x3fb8aa3b, v0
	v_exp_f32_e32 v15, v15
	v_exp_f32_e32 v0, v0
	v_mul_f32_e32 v13, v232, v15
	v_fmac_f32_e32 v13, v12, v0
	v_mov_b32_e32 v12, v13
	v_mov_b32_e32 v0, v14
	s_waitcnt vmcnt(6)
	v_mov_b32_e32 v52, v12
	v_add_f32_e32 v0, v0, v105
	v_max_f32_e32 v14, v111, v111
	v_max_f32_e32 v14, v0, v14
	v_sub_f32_e32 v15, v111, v14
	v_sub_f32_e32 v0, v0, v14
	v_mul_f32_e32 v15, 0x3fb8aa3b, v15
	v_mul_f32_e32 v0, 0x3fb8aa3b, v0
	v_exp_f32_e32 v15, v15
	v_exp_f32_e32 v0, v0
	v_mul_f32_e32 v13, v233, v15
	v_fmac_f32_e32 v13, v12, v0
	v_mov_b32_e32 v12, v13
	v_mov_b32_e32 v0, v14
	s_waitcnt vmcnt(3)
	v_mov_b32_e32 v54, v12
	v_add_f32_e32 v0, v0, v106
	v_max_f32_e32 v14, v112, v112
	v_max_f32_e32 v14, v0, v14
	v_sub_f32_e32 v15, v112, v14
	v_sub_f32_e32 v0, v0, v14
	v_mul_f32_e32 v15, 0x3fb8aa3b, v15
	v_mul_f32_e32 v0, 0x3fb8aa3b, v0
	v_exp_f32_e32 v15, v15
	v_exp_f32_e32 v0, v0
	v_mul_f32_e32 v13, v234, v15
	v_fmac_f32_e32 v13, v12, v0
	v_mov_b32_e32 v12, v13
	v_mov_b32_e32 v0, v14
	s_waitcnt vmcnt(0)
	v_mov_b32_e32 v55, v12
	v_add_f32_e32 v0, v0, v107
	v_max_f32_e32 v14, v113, v113
	v_max_f32_e32 v14, v0, v14
	v_sub_f32_e32 v15, v113, v14
	v_sub_f32_e32 v0, v0, v14
	v_mul_f32_e32 v15, 0x3fb8aa3b, v15
	v_mul_f32_e32 v0, 0x3fb8aa3b, v0
	v_exp_f32_e32 v15, v15
	v_exp_f32_e32 v0, v0
	v_mul_f32_e32 v13, v235, v15
	v_fmac_f32_e32 v13, v12, v0
	v_mov_b32_e32 v12, v13
	v_mov_b32_e32 v0, v14
	global_store_dword v[6:7], v236, off offset:-1024
	global_store_dword v[6:7], v237, off offset:-512
	global_store_dword v[6:7], v238, off
	global_store_dword v[6:7], v239, off offset:512
	global_store_dword v[6:7], v240, off offset:1024
	global_store_dword v[6:7], v241, off offset:1536
	global_store_dword v[6:7], v242, off offset:2048
	global_store_dword v[6:7], v243, off offset:2560
	global_store_dword v[88:89], v244, off offset:-1024
	global_store_dword v[88:89], v245, off offset:-512
	global_store_dword v[88:89], v246, off
	global_store_dword v[88:89], v247, off offset:512
	global_store_dword v[88:89], v248, off offset:1024
	global_store_dword v[88:89], v249, off offset:1536
	global_store_dword v[88:89], v250, off offset:2048
	global_store_dword v[88:89], v251, off offset:2560
	global_store_dword v[90:91], v132, off offset:-1024
	global_store_dword v[90:91], v133, off offset:-512
	global_store_dword v[90:91], v134, off
	global_store_dword v[90:91], v135, off offset:512
	global_store_dword v[90:91], v136, off offset:1024
	global_store_dword v[90:91], v137, off offset:1536
	global_store_dword v[90:91], v46, off offset:2048
	global_store_dword v[90:91], v47, off offset:2560
	global_store_dword v[92:93], v48, off offset:-1024
	global_store_dword v[92:93], v49, off offset:-512
	global_store_dword v[92:93], v65, off
	global_store_dword v[92:93], v66, off offset:512
	global_store_dword v[92:93], v67, off offset:1024
	global_store_dword v[92:93], v52, off offset:1536
	global_store_dword v[92:93], v54, off offset:2048
	global_store_dword v[92:93], v55, off offset:2560
	s_mov_b32 s2, 0
